# rnn pass 2 next-unit input prefetch (saddr loads into spare registers); GEMM loop mid-segment setprio pair removed
# speedup vs baseline: 1.0250x; 1.0028x over previous
; DI void rnn_phase(LAS unsigned char* lds, bf16_t* P, const bf16_t* WaT, const bf16_t* WiT, const float* convw, const float* convb, const float* ba, const float* bi, const float* lam,
;                   f32x2* sums, unsigned* au, bool fin, int bx, int G, int tid, int wid, int lane) {
;     ...
;         for (int u2 = bx; u2 < NU; u2 += G) {
;             const int hbk = u2 & 15, c = (u2 >> 4) & 63, b = u2 >> 10;
;             const size_t rowbase = (size_t)b * SEQ + c * 128; const int ch0 = hbk * 64, ch = lane, seg = wid;
;             const unsigned* aup = au + (rowbase + 16 * seg) * D + ch0 + ch;
;             bf16_t* yp = P + (rowbase + 16 * seg) * DIN + PC_Y + ch0 + ch;
;             unsigned w[16]; unsigned short yv[16];
; #pragma unroll
;             for (int j = 0; j < 16; ++j) { w[j] = aup[(size_t)j * D]; yv[j] = yp[(size_t)j * DIN]; }
;             float Ap = 1.f, Hp = 0.f;
; #pragma unroll
;             for (int k = 0; k < 8; ++k) { const int j = 8 * wid + k; if (j < c) { const f32x2 sv = sums[((size_t)b * NCH + j) * D + ch0 + lane]; Hp = sv.x * Hp + sv.y; Ap *= sv.x; } }
.LBB0_365:
	s_andn2_b64 vcc, exec, s[36:37]
	s_cbranch_vccnz .LBB0_388
	v_readlane_b32 s0, v236, 62
	v_readlane_b32 s1, v236, 63
	s_andn2_b64 vcc, exec, s[0:1]
	s_cbranch_vccnz .LBB0_387
	s_lshl_b32 s12, s7, 4
	s_ashr_i32 s18, s12, 31
	s_lshl_b32 s0, s7, 3
	s_lshl_b32 s19, s7, 8
	s_cmp_gt_i32 s7, 0
	s_cselect_b64 s[30:31], -1, 0
	s_or_b32 s40, s0, 1
	s_or_b32 s48, s0, 2
	s_or_b32 s52, s0, 3
	s_or_b32 s56, s0, 4
	s_or_b32 s60, s0, 5
	s_or_b32 s64, s0, 6
	s_or_b32 s68, s0, 7
	s_ashr_i32 s1, s0, 31
	s_ashr_i32 s41, s40, 31
	s_ashr_i32 s49, s48, 31
	s_ashr_i32 s53, s52, 31
	s_ashr_i32 s57, s56, 31
	s_ashr_i32 s61, s60, 31
	s_ashr_i32 s65, s64, 31
	s_ashr_i32 s69, s68, 31
	s_mov_b32 s20, 0
	v_writelane_b32 v234, s20, 6
	s_lshl_b64 s[36:37], s[0:1], 13
	s_lshl_b64 s[46:47], s[40:41], 13
	s_lshl_b64 s[50:51], s[48:49], 13
	s_lshl_b64 s[54:55], s[52:53], 13
	s_lshl_b64 s[58:59], s[56:57], 13
	s_lshl_b64 s[62:63], s[60:61], 13
	s_lshl_b64 s[66:67], s[64:65], 13
	s_lshl_b64 s[70:71], s[68:69], 13
	s_mov_b32 s1, s28
	s_branch .LBB0_369

; DI void rnn_phase(LAS unsigned char* lds, bf16_t* P, const bf16_t* WaT, const bf16_t* WiT, const float* convw, const float* convb, const float* ba, const float* bi, const float* lam,
;                   f32x2* sums, unsigned* au, bool fin, int bx, int G, int tid, int wid, int lane) {
;     ...
;             const size_t rowbase = (size_t)b * SEQ + c * 128; const int ch0 = hbk * 64, ch = lane, seg = wid;
;             const unsigned* aup = au + (rowbase + 16 * seg) * D + ch0 + ch;
;             bf16_t* yp = P + (rowbase + 16 * seg) * DIN + PC_Y + ch0 + ch;
;             unsigned w[16]; unsigned short yv[16];
; #pragma unroll
;             for (int j = 0; j < 16; ++j) { w[j] = aup[(size_t)j * D]; yv[j] = yp[(size_t)j * DIN]; }
;             float Ap = 1.f, Hp = 0.f;
; #pragma unroll
;             for (int k = 0; k < 8; ++k) { const int j = 8 * wid + k; if (j < c) { const f32x2 sv = sums[((size_t)b * NCH + j) * D + ch0 + lane]; Hp = sv.x * Hp + sv.y; Ap *= sv.x; } }
.LBB0_369:
	s_ashr_i32 s38, s1, 10
	s_bfe_u32 s21, s1, 0x60004
	s_ashr_i32 s39, s38, 31
	s_lshl_b32 s22, s1, 6
	s_lshl_b64 s[72:73], s[38:39], 13
	s_lshl_b32 s23, s21, 7
	s_and_b32 s22, s22, 0x3c0
	s_add_u32 s25, s72, s12
	s_addc_u32 s41, s73, s18
	s_add_u32 s72, s25, s23
	s_addc_u32 s73, s41, 0
	s_lshl_b64 s[74:75], s[72:73], 12
	s_add_u32 s23, s44, s74
	s_addc_u32 s25, s45, s75
	s_lshl_b32 s41, s22, 2
	s_add_u32 s74, s23, s41
	s_addc_u32 s75, s25, 0
	s_mul_i32 s23, s73, 0x3c00
	s_mul_hi_u32 s25, s72, 0x3c00
	s_add_i32 s25, s25, s23
	s_mul_i32 s23, s72, 0x3c00
	s_add_u32 s23, s42, s23
	v_lshlrev_b32_e32 v80, 2, v64
	s_addc_u32 s25, s43, s25
	s_lshl_b32 s41, s22, 1
	v_lshl_add_u64 v[2:3], s[74:75], 0, v[80:81]
	s_add_u32 s72, s23, s41
	s_addc_u32 s73, s25, 0
	v_lshlrev_b32_e32 v80, 1, v64
	v_add_co_u32_e32 v4, vcc, s15, v2
	v_lshl_add_u64 v[0:1], s[72:73], 0, v[80:81]
	s_lshl_b64 s[38:39], s[38:39], 19
	v_lshlrev_b32_e32 v80, 3, v64
	s_add_u32 s23, s16, s38
	s_addc_u32 s25, s17, s39
	s_lshl_b32 s22, s22, 3
	s_add_u32 s22, s23, s22
	s_addc_u32 s23, s25, 0
	v_readlane_b32 s25, v234, 6
	v_lshlrev_b32_e32 v5, 2, v64
	v_lshlrev_b32_e32 v6, 1, v64
	s_cmp_lg_u32 s25, 0
	s_cbranch_scc1 .Lr2_movs
	v_add_u32_e32 v4, 0x0, v5
	global_load_dword v53, v4, s[74:75]
	v_add_u32_e32 v4, 0x1000, v5
	global_load_dword v56, v4, s[74:75]
	v_add_u32_e32 v4, 0x2000, v5
	global_load_dword v60, v4, s[74:75]
	v_add_u32_e32 v4, 0x3000, v5
	global_load_dword v62, v4, s[74:75]
	v_add_u32_e32 v4, 0x4000, v5
	global_load_dword v63, v4, s[74:75]
	v_add_u32_e32 v4, 0x5000, v5
	global_load_dword v65, v4, s[74:75]
	v_add_u32_e32 v4, 0x6000, v5
	global_load_dword v67, v4, s[74:75]
	v_add_u32_e32 v4, 0x7000, v5
	global_load_dword v68, v4, s[74:75]
	v_add_u32_e32 v4, 0x8000, v5
	global_load_dword v69, v4, s[74:75]
	v_add_u32_e32 v4, 0x9000, v5
	global_load_dword v70, v4, s[74:75]
	v_add_u32_e32 v4, 0xa000, v5
	global_load_dword v71, v4, s[74:75]
	v_add_u32_e32 v4, 0xb000, v5
	global_load_dword v73, v4, s[74:75]
	v_add_u32_e32 v4, 0xc000, v5
	global_load_dword v74, v4, s[74:75]
	v_add_u32_e32 v4, 0xd000, v5
	global_load_dword v75, v4, s[74:75]
	v_add_u32_e32 v4, 0xe000, v5
	global_load_dword v77, v4, s[74:75]
	v_add_u32_e32 v4, 0xf000, v5
	global_load_dword v78, v4, s[74:75]
	v_add_u32_e32 v4, 0x800, v6
	global_load_ushort v58, v4, s[72:73]
	v_add_u32_e32 v4, 0x4400, v6
	global_load_ushort v55, v4, s[72:73]
	v_add_u32_e32 v4, 0x8000, v6
	global_load_ushort v51, v4, s[72:73]
	v_add_u32_e32 v4, 0xbc00, v6
	global_load_ushort v49, v4, s[72:73]
	v_add_u32_e32 v4, 0xf800, v6
	global_load_ushort v47, v4, s[72:73]
	v_add_u32_e32 v4, 0x13400, v6
	global_load_ushort v44, v4, s[72:73]
	v_add_u32_e32 v4, 0x17000, v6
	global_load_ushort v43, v4, s[72:73]
	v_add_u32_e32 v4, 0x1ac00, v6
	global_load_ushort v42, v4, s[72:73]
	v_add_u32_e32 v4, 0x1e800, v6
	global_load_ushort v41, v4, s[72:73]
	v_add_u32_e32 v4, 0x22400, v6
	global_load_ushort v40, v4, s[72:73]
	v_add_u32_e32 v4, 0x26000, v6
	global_load_ushort v39, v4, s[72:73]
	v_add_u32_e32 v4, 0x29c00, v6
	global_load_ushort v38, v4, s[72:73]
	v_add_u32_e32 v4, 0x2d800, v6
	global_load_ushort v37, v4, s[72:73]
	v_add_u32_e32 v4, 0x31400, v6
	global_load_ushort v36, v4, s[72:73]
	v_add_u32_e32 v4, 0x35000, v6
	global_load_ushort v35, v4, s[72:73]
	v_add_u32_e32 v4, 0x38c00, v6
	global_load_ushort v34, v4, s[72:73]
	s_branch .Lr2_loaded
.Lr2_movs:
	s_waitcnt vmcnt(16)
	v_mov_b32_e32 v53, v176
	v_mov_b32_e32 v56, v177
	v_mov_b32_e32 v60, v178
	v_mov_b32_e32 v62, v179
	v_mov_b32_e32 v63, v180
	v_mov_b32_e32 v65, v181
	v_mov_b32_e32 v67, v182
	v_mov_b32_e32 v68, v183
	v_mov_b32_e32 v69, v184
	v_mov_b32_e32 v70, v185
	v_mov_b32_e32 v71, v186
	v_mov_b32_e32 v73, v187
	v_mov_b32_e32 v74, v188
	v_mov_b32_e32 v75, v189
	v_mov_b32_e32 v77, v190
	v_mov_b32_e32 v78, v191
	v_mov_b32_e32 v58, v192
	v_mov_b32_e32 v55, v193
	v_mov_b32_e32 v51, v194
	v_mov_b32_e32 v49, v195
	v_mov_b32_e32 v47, v196
	v_mov_b32_e32 v44, v197
	v_mov_b32_e32 v43, v198
	v_mov_b32_e32 v42, v199
	v_mov_b32_e32 v41, v200
	v_mov_b32_e32 v40, v201
	v_mov_b32_e32 v39, v202
	v_mov_b32_e32 v38, v203
	v_mov_b32_e32 v37, v204
	v_mov_b32_e32 v36, v205
	v_mov_b32_e32 v35, v206
	v_mov_b32_e32 v34, v207
.Lr2_loaded:
	v_lshl_add_u64 v[4:5], s[22:23], 0, v[80:81]
	v_lshl_add_u64 v[92:93], v[4:5], 0, s[36:37]
	v_lshl_add_u64 v[94:95], v[4:5], 0, s[46:47]
	v_lshl_add_u64 v[96:97], v[4:5], 0, s[50:51]
	v_lshl_add_u64 v[98:99], v[4:5], 0, s[54:55]
	v_lshl_add_u64 v[100:101], v[4:5], 0, s[58:59]
	v_lshl_add_u64 v[102:103], v[4:5], 0, s[62:63]
	v_lshl_add_u64 v[104:105], v[4:5], 0, s[66:67]
	v_lshl_add_u64 v[106:107], v[4:5], 0, s[70:71]
	global_load_dwordx2 v[108:109], v[92:93], off
	global_load_dwordx2 v[110:111], v[94:95], off
	global_load_dwordx2 v[112:113], v[96:97], off
	global_load_dwordx2 v[114:115], v[98:99], off
	global_load_dwordx2 v[116:117], v[100:101], off
	global_load_dwordx2 v[118:119], v[102:103], off
	global_load_dwordx2 v[120:121], v[104:105], off
	global_load_dwordx2 v[122:123], v[106:107], off
	v_mov_b32_e32 v2, 1.0
	v_mov_b32_e32 v3, 0
	s_cmp_lt_i32 s0, s21
	s_cselect_b64 vcc, -1, 0
	s_waitcnt vmcnt(7)
	v_cndmask_b32_e32 v108, 1.0, v108, vcc
	v_cndmask_b32_e32 v109, 0, v109, vcc
	v_fmac_f32_e32 v109, v3, v108
	v_mul_f32_e32 v2, v2, v108
	v_mov_b32_e32 v3, v109
	s_cmp_lt_i32 s40, s21
	s_cselect_b64 vcc, -1, 0
	s_waitcnt vmcnt(6)
	v_cndmask_b32_e32 v110, 1.0, v110, vcc
	v_cndmask_b32_e32 v111, 0, v111, vcc
	v_fmac_f32_e32 v111, v3, v110
	v_mul_f32_e32 v2, v2, v110
	v_mov_b32_e32 v3, v111
	s_cmp_lt_i32 s48, s21
	s_cselect_b64 vcc, -1, 0
	s_waitcnt vmcnt(5)
	v_cndmask_b32_e32 v112, 1.0, v112, vcc
	v_cndmask_b32_e32 v113, 0, v113, vcc
	v_fmac_f32_e32 v113, v3, v112
	v_mul_f32_e32 v2, v2, v112
	v_mov_b32_e32 v3, v113
	s_cmp_lt_i32 s52, s21
	s_cselect_b64 vcc, -1, 0
	s_waitcnt vmcnt(4)
	v_cndmask_b32_e32 v114, 1.0, v114, vcc
	v_cndmask_b32_e32 v115, 0, v115, vcc
	v_fmac_f32_e32 v115, v3, v114
	v_mul_f32_e32 v2, v2, v114
	v_mov_b32_e32 v3, v115
	s_cmp_lt_i32 s56, s21
	s_cselect_b64 vcc, -1, 0
	s_waitcnt vmcnt(3)
	v_cndmask_b32_e32 v116, 1.0, v116, vcc
	v_cndmask_b32_e32 v117, 0, v117, vcc
	v_fmac_f32_e32 v117, v3, v116
	v_mul_f32_e32 v2, v2, v116
	v_mov_b32_e32 v3, v117
	s_cmp_lt_i32 s60, s21
	s_cselect_b64 vcc, -1, 0
	s_waitcnt vmcnt(2)
	v_cndmask_b32_e32 v118, 1.0, v118, vcc
	v_cndmask_b32_e32 v119, 0, v119, vcc
	v_fmac_f32_e32 v119, v3, v118
	v_mul_f32_e32 v2, v2, v118
	v_mov_b32_e32 v3, v119
	s_cmp_lt_i32 s64, s21
	s_cselect_b64 vcc, -1, 0
	s_waitcnt vmcnt(1)
	v_cndmask_b32_e32 v120, 1.0, v120, vcc
	v_cndmask_b32_e32 v121, 0, v121, vcc
	v_fmac_f32_e32 v121, v3, v120
	v_mul_f32_e32 v2, v2, v120
	v_mov_b32_e32 v3, v121
	s_cmp_lt_i32 s68, s21
	s_cselect_b64 vcc, -1, 0
	s_waitcnt vmcnt(0)
	v_cndmask_b32_e32 v122, 1.0, v122, vcc
	v_cndmask_b32_e32 v123, 0, v123, vcc
	v_fmac_f32_e32 v123, v3, v122
	v_mul_f32_e32 v2, v2, v122
	v_mov_b32_e32 v3, v123
; #define LAS __attribute__((address_space(3)))
; DI void rnn_phase(LAS unsigned char* lds, bf16_t* P, const bf16_t* WaT, const bf16_t* WiT, const float* convw, const float* convb, const float* ba, const float* bi, const float* lam,
;                   f32x2* sums, unsigned* au, bool fin, int bx, int G, int tid, int wid, int lane) {
;     ...
;             for (int j = 0; j < 16; ++j) { w[j] = aup[(size_t)j * D]; yv[j] = yp[(size_t)j * DIN]; }
;             float Ap = 1.f, Hp = 0.f;
; #pragma unroll
;             for (int k = 0; k < 8; ++k) { const int j = 8 * wid + k; if (j < c) { const f32x2 sv = sums[((size_t)b * NCH + j) * D + ch0 + lane]; Hp = sv.x * Hp + sv.y; Ap *= sv.x; } }
;             float av[16], uv[16]; float A = 1.f, H = 0.f;
; #pragma unroll
;             for (int j = 0; j < 16; ++j) { const h2_t v = __builtin_bit_cast(h2_t, w[j]); av[j] = 1.0f - (float)v.x; uv[j] = (float)v.y; H = av[j] * H + uv[j]; A *= av[j]; }
;             LAS float* SGp = SG + (par ? 2048 : 0);
;             SGp[seg * 64 + ch] = A; SGp[512 + seg * 64 + ch] = H; SGp[1024 + wid * 64 + lane] = Ap; SGp[1536 + wid * 64 + lane] = Hp;
;             __syncthreads();
;             float h = 0.f;
; #pragma unroll
;             for (int q8 = 0; q8 < 8; ++q8) h = SGp[1024 + q8 * 64 + ch] * h + SGp[1536 + q8 * 64 + ch];
;             for (int s2 = 0; s2 < seg; ++s2) h = SGp[s2 * 64 + ch] * h + SGp[512 + s2 * 64 + ch];
.LBB0_380:
	s_waitcnt vmcnt(0) lgkmcnt(0)
	s_add_i32 s25, s1, s29
	s_cmpk_gt_i32 s25, 0x7ff
	s_cbranch_scc1 .Lr2_nopf
	s_lshl_b32 s25, s29, 15
	s_add_u32 s22, s74, s25
	s_addc_u32 s23, s75, 0
	s_mul_i32 s25, s29, 0x1e000
	s_add_u32 s38, s72, s25
	s_addc_u32 s39, s73, 0
	v_lshlrev_b32_e32 v125, 2, v64
	v_lshlrev_b32_e32 v126, 1, v64
	v_add_u32_e32 v124, 0x0, v125
	global_load_dword v176, v124, s[22:23]
	v_add_u32_e32 v124, 0x1000, v125
	global_load_dword v177, v124, s[22:23]
	v_add_u32_e32 v124, 0x2000, v125
	global_load_dword v178, v124, s[22:23]
	v_add_u32_e32 v124, 0x3000, v125
	global_load_dword v179, v124, s[22:23]
	v_add_u32_e32 v124, 0x4000, v125
	global_load_dword v180, v124, s[22:23]
	v_add_u32_e32 v124, 0x5000, v125
	global_load_dword v181, v124, s[22:23]
	v_add_u32_e32 v124, 0x6000, v125
	global_load_dword v182, v124, s[22:23]
	v_add_u32_e32 v124, 0x7000, v125
	global_load_dword v183, v124, s[22:23]
	v_add_u32_e32 v124, 0x8000, v125
	global_load_dword v184, v124, s[22:23]
	v_add_u32_e32 v124, 0x9000, v125
	global_load_dword v185, v124, s[22:23]
	v_add_u32_e32 v124, 0xa000, v125
	global_load_dword v186, v124, s[22:23]
	v_add_u32_e32 v124, 0xb000, v125
	global_load_dword v187, v124, s[22:23]
	v_add_u32_e32 v124, 0xc000, v125
	global_load_dword v188, v124, s[22:23]
	v_add_u32_e32 v124, 0xd000, v125
	global_load_dword v189, v124, s[22:23]
	v_add_u32_e32 v124, 0xe000, v125
	global_load_dword v190, v124, s[22:23]
	v_add_u32_e32 v124, 0xf000, v125
	global_load_dword v191, v124, s[22:23]
	v_add_u32_e32 v124, 0x800, v126
	global_load_ushort v192, v124, s[38:39]
	v_add_u32_e32 v124, 0x4400, v126
	global_load_ushort v193, v124, s[38:39]
	v_add_u32_e32 v124, 0x8000, v126
	global_load_ushort v194, v124, s[38:39]
	v_add_u32_e32 v124, 0xbc00, v126
	global_load_ushort v195, v124, s[38:39]
	v_add_u32_e32 v124, 0xf800, v126
	global_load_ushort v196, v124, s[38:39]
	v_add_u32_e32 v124, 0x13400, v126
	global_load_ushort v197, v124, s[38:39]
	v_add_u32_e32 v124, 0x17000, v126
	global_load_ushort v198, v124, s[38:39]
	v_add_u32_e32 v124, 0x1ac00, v126
	global_load_ushort v199, v124, s[38:39]
	v_add_u32_e32 v124, 0x1e800, v126
	global_load_ushort v200, v124, s[38:39]
	v_add_u32_e32 v124, 0x22400, v126
	global_load_ushort v201, v124, s[38:39]
	v_add_u32_e32 v124, 0x26000, v126
	global_load_ushort v202, v124, s[38:39]
	v_add_u32_e32 v124, 0x29c00, v126
	global_load_ushort v203, v124, s[38:39]
	v_add_u32_e32 v124, 0x2d800, v126
	global_load_ushort v204, v124, s[38:39]
	v_add_u32_e32 v124, 0x31400, v126
	global_load_ushort v205, v124, s[38:39]
	v_add_u32_e32 v124, 0x35000, v126
	global_load_ushort v206, v124, s[38:39]
	v_add_u32_e32 v124, 0x38c00, v126
	global_load_ushort v207, v124, s[38:39]
	s_mov_b32 s25, 1
	s_branch .Lr2_pfset
.Lr2_nopf:
	s_mov_b32 s25, 0
.Lr2_pfset:
	s_nop 0
	v_writelane_b32 v234, s25, 6
	v_cvt_f32_f16_e32 v6, v60
	v_cvt_f32_f16_e32 v4, v53
	v_cvt_f32_f16_e32 v5, v56
	s_cmp_eq_u32 s20, 0
	v_sub_f32_e32 v80, 1.0, v6
	v_cvt_f32_f16_e32 v6, v62
	v_sub_f32_e32 v83, 1.0, v4
	v_fma_mix_f32 v4, v83, 0, v53 op_sel:[0,0,1] op_sel_hi:[0,0,1]
	v_sub_f32_e32 v82, 1.0, v5
	v_sub_f32_e32 v79, 1.0, v6
	v_cvt_f32_f16_e32 v6, v63
	v_fma_mix_f32 v4, v4, v82, v56 op_sel:[0,0,1] op_sel_hi:[0,0,1]
	v_mul_f32_e32 v5, v83, v82
	v_fma_mix_f32 v4, v4, v80, v60 op_sel:[0,0,1] op_sel_hi:[0,0,1]
	v_sub_f32_e32 v76, 1.0, v6
	v_cvt_f32_f16_e32 v6, v65
	v_mul_f32_e32 v5, v5, v80
	v_fma_mix_f32 v4, v4, v79, v62 op_sel:[0,0,1] op_sel_hi:[0,0,1]
	v_mul_f32_e32 v5, v5, v79
	v_sub_f32_e32 v72, 1.0, v6
	v_cvt_f32_f16_e32 v6, v67
	v_fma_mix_f32 v4, v4, v76, v63 op_sel:[0,0,1] op_sel_hi:[0,0,1]
	v_mul_f32_e32 v5, v5, v76
	v_fma_mix_f32 v4, v4, v72, v65 op_sel:[0,0,1] op_sel_hi:[0,0,1]
	v_sub_f32_e32 v66, 1.0, v6
	v_cvt_f32_f16_e32 v6, v68
	v_mul_f32_e32 v5, v5, v72
	v_fma_mix_f32 v4, v4, v66, v67 op_sel:[0,0,1] op_sel_hi:[0,0,1]
	v_mul_f32_e32 v5, v5, v66
	v_sub_f32_e32 v61, 1.0, v6
	v_cvt_f32_f16_e32 v6, v69
	v_fma_mix_f32 v4, v4, v61, v68 op_sel:[0,0,1] op_sel_hi:[0,0,1]
	v_mul_f32_e32 v5, v5, v61
	s_cselect_b32 s21, 0, 0x2000
	v_sub_f32_e32 v59, 1.0, v6
	v_cvt_f32_f16_e32 v6, v70
	v_fma_mix_f32 v4, v4, v59, v69 op_sel:[0,0,1] op_sel_hi:[0,0,1]
	v_mul_f32_e32 v5, v5, v59
	s_add_i32 s21, s21, 0
	v_sub_f32_e32 v57, 1.0, v6
	v_cvt_f32_f16_e32 v6, v71
	v_fma_mix_f32 v4, v4, v57, v70 op_sel:[0,0,1] op_sel_hi:[0,0,1]
	v_mul_f32_e32 v5, v5, v57
	s_add_i32 s21, s21, 0x19000
	v_sub_f32_e32 v54, 1.0, v6
	v_cvt_f32_f16_e32 v6, v73
	v_fma_mix_f32 v4, v4, v54, v71 op_sel:[0,0,1] op_sel_hi:[0,0,1]
	v_mul_f32_e32 v5, v5, v54
	s_add_i32 s22, s21, s19
	v_sub_f32_e32 v52, 1.0, v6
	v_cvt_f32_f16_e32 v6, v74
	v_fma_mix_f32 v4, v4, v52, v73 op_sel:[0,0,1] op_sel_hi:[0,0,1]
	v_mul_f32_e32 v5, v5, v52
	s_andn2_b64 vcc, exec, s[30:31]
	v_sub_f32_e32 v50, 1.0, v6
	v_cvt_f32_f16_e32 v6, v75
	v_fma_mix_f32 v4, v4, v50, v74 op_sel:[0,0,1] op_sel_hi:[0,0,1]
	v_mul_f32_e32 v5, v5, v50
	v_sub_f32_e32 v48, 1.0, v6
	v_cvt_f32_f16_e32 v6, v77
	v_fma_mix_f32 v4, v4, v48, v75 op_sel:[0,0,1] op_sel_hi:[0,0,1]
	v_mul_f32_e32 v5, v5, v48
	v_sub_f32_e32 v46, 1.0, v6
	v_cvt_f32_f16_e32 v6, v78
	v_fma_mix_f32 v4, v4, v46, v77 op_sel:[0,0,1] op_sel_hi:[0,0,1]
	v_mul_f32_e32 v5, v5, v46
	v_sub_f32_e32 v45, 1.0, v6
	v_lshlrev_b32_e32 v6, 2, v64
	v_fma_mix_f32 v4, v4, v45, v78 op_sel:[0,0,1] op_sel_hi:[0,0,1]
	v_mul_f32_e32 v5, v5, v45
	v_add_u32_e32 v7, s22, v6
	ds_write2st64_b32 v7, v5, v4 offset1:8
	ds_write2st64_b32 v7, v2, v3 offset0:16 offset1:24
	v_add_u32_e32 v2, s21, v6
	s_waitcnt lgkmcnt(0)
	s_barrier
	ds_read2st64_b32 v[4:5], v2 offset0:16 offset1:17
	ds_read2st64_b32 v[6:7], v2 offset0:24 offset1:25
	s_mov_b32 s21, s7
	s_waitcnt lgkmcnt(0)
	v_fma_f32 v3, 0, v4, v6
	v_fmac_f32_e32 v7, v3, v5
	ds_read2st64_b32 v[4:5], v2 offset0:18 offset1:19
	ds_read2st64_b32 v[8:9], v2 offset0:26 offset1:27
	s_waitcnt lgkmcnt(0)
	v_fma_f32 v3, v7, v4, v8
	v_fmac_f32_e32 v9, v3, v5
	ds_read2st64_b32 v[4:5], v2 offset0:20 offset1:21
	ds_read2st64_b32 v[6:7], v2 offset0:28 offset1:29
	s_waitcnt lgkmcnt(0)
	v_fma_f32 v3, v9, v4, v6
	v_fmac_f32_e32 v7, v3, v5
	ds_read2st64_b32 v[4:5], v2 offset0:22 offset1:23
	ds_read2st64_b32 v[30:31], v2 offset0:30 offset1:31
	s_waitcnt lgkmcnt(0)
	v_fma_f32 v3, v7, v4, v30
	v_fmac_f32_e32 v31, v3, v5
	s_cbranch_vccnz .LBB0_368

; #define PG8_STAGE(bufoff, gbase, voff) do { _Pragma("unroll") for (int _i = 0; _i < 2; ++_i) \
;         __builtin_amdgcn_global_load_lds((const unsigned*)((const char*)(gbase) + (voff)[_i]), (LAS unsigned*)(lds + (bufoff) + ldsw + _i * 8192), 16, 0, 0); } while (0)
; #define PG8_LDA(dst, b, h) do { _Pragma("unroll") for (int m = 0; m < 4; ++m) _Pragma("unroll") for (int k = 0; k < 2; ++k) dst[m][k] = *(const LAS bf16x8*)(lds + PG8_SA(b, h) + aoff + m * 2048 + k * 1024); } while (0)
; #define PG8_LDB(dst, b, h) do { _Pragma("unroll") for (int n = 0; n < 2; ++n) _Pragma("unroll") for (int k = 0; k < 2; ++k) dst[n][k] = *(const LAS bf16x8*)(lds + PG8_SB(b, h) + boff + n * 2048 + k * 1024); } while (0)
; #define PG8_MMA(ai, bj, At, Bt) do { __builtin_amdgcn_s_setprio(1); _Pragma("unroll") for (int m = 0; m < 4; ++m) _Pragma("unroll") for (int n = 0; n < 2; ++n) _Pragma("unroll") for (int k = 0; k < 2; ++k) \
;         acc[ai][bj][m][n] = __builtin_amdgcn_mfma_f32_16x16x32_bf16(Bt[n][k], At[m][k], acc[ai][bj][m][n], 0, 0, 0); __builtin_amdgcn_s_setprio(0); } while (0)
; #define PG8_WAIT_V(n) asm volatile("s_waitcnt vmcnt(" #n ")" ::: "memory")
; #define PG8_WAIT_L(n) asm volatile("s_waitcnt lgkmcnt(" #n ")" ::: "memory")
; #define PG8_BAR __builtin_amdgcn_s_barrier()
; DI void gemm_phase(LAS unsigned char* lds, int ph, unsigned char* ws, unsigned char* wg, int l, const float* pscale, int G, int cidx, int nx) {
;     ...
;             const char* a1 = PG8_KA(t + 1);
;             const char* a2 = last ? nA : PG8_KA(t + 2); const char* b2 = last ? nB : PG8_KB(t + 2);
;             const char* a3 = a2 + kstep; const char* b3 = b2 + kstep;
;             if (zAb != 0 && t != 0 && (t & ntzm) == 0) { unsigned char* wsx = ws; asm volatile("" : "+s"(wsx)); int frx = fr; asm volatile("" : "+v"(frx)); merge_carry(acc, wsx, cur, (t >> lz) - 1, wr, wc, frx, fq); }
;             PG8_LDB(B0, 0, 0); PG8_LDB(B1, 0, 1); PG8_SCHED; PG8_LDA(At, 0, 0); PG8_STAGE(PG8_SA(1, 1), a1 + hstepA, voffA);
;             PG8_WAIT_V(8); PG8_WAIT_L(0); PG8_BAR; PG8_MMA(0, 0, At, B0); PG8_MMA(0, 1, At, B1); PG8_BAR; PG8_SCHED;
;             PG8_LDA(At, 0, 1); PG8_STAGE(PG8_SB(0, 0), b2, voffB); PG8_STAGE(PG8_SB(0, 1), b2 + hstepB, voffB); PG8_STAGE(PG8_SA(0, 0), a2, voffA);
;             PG8_WAIT_V(8); PG8_WAIT_L(0); PG8_BAR; PG8_MMA(1, 0, At, B0); PG8_MMA(1, 1, At, B1); PG8_BAR; PG8_SCHED;
.LBB0_500:
	s_add_i32 s12, s38, 1
	s_lshr_b32 s18, s12, s76
	s_mul_i32 s19, s53, s18
	s_mul_hi_u32 s20, s52, s18
	s_add_i32 s20, s20, s19
	s_mul_i32 s18, s52, s18
	s_add_u32 s18, s42, s18
	s_addc_u32 s19, s43, s20
	s_and_b32 s12, s12, s83
	s_lshl_b32 s12, s12, 7
	s_add_u32 s12, s18, s12
	s_addc_u32 s19, s19, 0
	v_add_u32_e32 v80, s91, v173
	s_add_i32 s20, 0, 0x14000
	ds_read_b128 v[132:135], v80
	ds_read_b128 v[136:139], v80 offset:1024
	ds_read_b128 v[142:145], v80 offset:2048
	ds_read_b128 v[158:161], v80 offset:3072
	v_add_u32_e32 v80, s20, v173
	ds_read_b128 v[176:179], v80
	ds_read_b128 v[180:183], v80 offset:1024
	ds_read_b128 v[184:187], v80 offset:2048
	ds_read_b128 v[188:191], v80 offset:3072
	s_add_u32 s18, s12, s7
	s_addc_u32 s19, s19, 0
	s_add_i32 m0, s79, 0xc000
	ds_read_b128 v[192:195], v174
	ds_read_b128 v[196:199], v174 offset:1024
	ds_read_b128 v[200:203], v174 offset:2048
	ds_read_b128 v[204:207], v174 offset:3072
	ds_read_b128 v[208:211], v174 offset:4096
	ds_read_b128 v[212:215], v174 offset:5120
	ds_read_b128 v[216:219], v174 offset:6144
	ds_read_b128 v[220:223], v174 offset:7168
	global_load_lds_dwordx4 v150, s[18:19]
	s_add_i32 m0, s79, 0xe000
	s_nop 0
	global_load_lds_dwordx4 v154, s[18:19]
	s_waitcnt vmcnt(8)
	s_waitcnt lgkmcnt(0)
	s_barrier
	s_setprio 1
	s_waitcnt lgkmcnt(0)
	v_mfma_f32_16x16x32_bf16 v[128:131], v[132:135], v[192:195], v[128:131]
	v_mfma_f32_16x16x32_bf16 v[124:127], v[142:145], v[192:195], v[124:127]
	v_mfma_f32_16x16x32_bf16 v[112:115], v[132:135], v[200:203], v[112:115]
	v_mfma_f32_16x16x32_bf16 v[108:111], v[142:145], v[200:203], v[108:111]
	v_mfma_f32_16x16x32_bf16 v[96:99], v[132:135], v[208:211], v[96:99]
	v_mfma_f32_16x16x32_bf16 v[92:95], v[142:145], v[208:211], v[92:95]
	v_mfma_f32_16x16x32_bf16 v[76:79], v[132:135], v[216:219], v[76:79]
	v_mfma_f32_16x16x32_bf16 v[72:75], v[142:145], v[216:219], v[72:75]
	v_mfma_f32_16x16x32_bf16 v[128:131], v[136:139], v[196:199], v[128:131]
	v_mfma_f32_16x16x32_bf16 v[124:127], v[158:161], v[196:199], v[124:127]
	v_mfma_f32_16x16x32_bf16 v[112:115], v[136:139], v[204:207], v[112:115]
	v_mfma_f32_16x16x32_bf16 v[108:111], v[158:161], v[204:207], v[108:111]
	v_mfma_f32_16x16x32_bf16 v[96:99], v[136:139], v[212:215], v[96:99]
	v_mfma_f32_16x16x32_bf16 v[92:95], v[158:161], v[212:215], v[92:95]
	v_mfma_f32_16x16x32_bf16 v[76:79], v[136:139], v[220:223], v[76:79]
	v_mfma_f32_16x16x32_bf16 v[72:75], v[158:161], v[220:223], v[72:75]
	v_mfma_f32_16x16x32_bf16 v[120:123], v[176:179], v[192:195], v[120:123]
	v_mfma_f32_16x16x32_bf16 v[116:119], v[184:187], v[192:195], v[116:119]
	v_mfma_f32_16x16x32_bf16 v[104:107], v[176:179], v[200:203], v[104:107]
	v_mfma_f32_16x16x32_bf16 v[100:103], v[184:187], v[200:203], v[100:103]
	v_mfma_f32_16x16x32_bf16 v[88:91], v[176:179], v[208:211], v[88:91]
	v_mfma_f32_16x16x32_bf16 v[82:85], v[184:187], v[208:211], v[84:87]
	v_mfma_f32_16x16x32_bf16 v[68:71], v[176:179], v[216:219], v[68:71]
	v_mfma_f32_16x16x32_bf16 v[64:67], v[184:187], v[216:219], v[64:67]
	v_mfma_f32_16x16x32_bf16 v[120:123], v[180:183], v[196:199], v[120:123]
	v_mfma_f32_16x16x32_bf16 v[116:119], v[188:191], v[196:199], v[116:119]
	v_mfma_f32_16x16x32_bf16 v[104:107], v[180:183], v[204:207], v[104:107]
	v_mfma_f32_16x16x32_bf16 v[100:103], v[188:191], v[204:207], v[100:103]
	v_mfma_f32_16x16x32_bf16 v[88:91], v[180:183], v[212:215], v[88:91]
	v_mfma_f32_16x16x32_bf16 v[82:85], v[188:191], v[212:215], v[82:85]
	v_mfma_f32_16x16x32_bf16 v[68:71], v[180:183], v[220:223], v[68:71]
	v_mfma_f32_16x16x32_bf16 v[64:67], v[188:191], v[220:223], v[64:67]
	s_setprio 0
	s_barrier
	s_add_i32 s12, s91, s78
	s_mov_b32 m0, s12
	ds_read_b128 v[192:195], v174 offset:16384
	ds_read_b128 v[196:199], v174 offset:17408
	ds_read_b128 v[200:203], v174 offset:18432
	ds_read_b128 v[204:207], v174 offset:19456
	ds_read_b128 v[208:211], v174 offset:20480
	ds_read_b128 v[212:215], v174 offset:21504
	ds_read_b128 v[216:219], v174 offset:22528
	ds_read_b128 v[220:223], v174 offset:23552
	global_load_lds_dwordx4 v152, s[64:65]
	s_add_i32 m0, s12, 0x2000
	s_add_u32 s18, s64, s77
	s_addc_u32 s19, s65, 0
	s_add_i32 s12, s20, s78
	global_load_lds_dwordx4 v156, s[64:65]
	s_mov_b32 m0, s12
	s_nop 0
	global_load_lds_dwordx4 v152, s[18:19]
	s_add_i32 m0, s12, 0x2000
	s_nop 0
	global_load_lds_dwordx4 v156, s[18:19]
	s_mov_b32 m0, s79
	s_nop 0
	global_load_lds_dwordx4 v150, s[0:1]
	s_mov_b32 m0, s80
	s_nop 0
	global_load_lds_dwordx4 v154, s[0:1]
	s_waitcnt vmcnt(8)
	s_waitcnt lgkmcnt(0)
	s_barrier
; #define PG8_STAGE(bufoff, gbase, voff) do { _Pragma("unroll") for (int _i = 0; _i < 2; ++_i) \
;         __builtin_amdgcn_global_load_lds((const unsigned*)((const char*)(gbase) + (voff)[_i]), (LAS unsigned*)(lds + (bufoff) + ldsw + _i * 8192), 16, 0, 0); } while (0)
; #define PG8_LDA(dst, b, h) do { _Pragma("unroll") for (int m = 0; m < 4; ++m) _Pragma("unroll") for (int k = 0; k < 2; ++k) dst[m][k] = *(const LAS bf16x8*)(lds + PG8_SA(b, h) + aoff + m * 2048 + k * 1024); } while (0)
; #define PG8_LDB(dst, b, h) do { _Pragma("unroll") for (int n = 0; n < 2; ++n) _Pragma("unroll") for (int k = 0; k < 2; ++k) dst[n][k] = *(const LAS bf16x8*)(lds + PG8_SB(b, h) + boff + n * 2048 + k * 1024); } while (0)
; #define PG8_MMA(ai, bj, At, Bt) do { __builtin_amdgcn_s_setprio(1); _Pragma("unroll") for (int m = 0; m < 4; ++m) _Pragma("unroll") for (int n = 0; n < 2; ++n) _Pragma("unroll") for (int k = 0; k < 2; ++k) \
;         acc[ai][bj][m][n] = __builtin_amdgcn_mfma_f32_16x16x32_bf16(Bt[n][k], At[m][k], acc[ai][bj][m][n], 0, 0, 0); __builtin_amdgcn_s_setprio(0); } while (0)
; #define PG8_WAIT_V(n) asm volatile("s_waitcnt vmcnt(" #n ")" ::: "memory")
; #define PG8_WAIT_L(n) asm volatile("s_waitcnt lgkmcnt(" #n ")" ::: "memory")
; #define PG8_BAR __builtin_amdgcn_s_barrier()
; #define PG8_SCHED __builtin_amdgcn_sched_barrier(0)
; DI void gemm_phase(LAS unsigned char* lds, int ph, unsigned char* ws, unsigned char* wg, int l, const float* pscale, int G, int cidx, int nx) {
;     ...
;             PG8_WAIT_V(8); PG8_WAIT_L(0); PG8_BAR; PG8_MMA(1, 0, At, B0); PG8_MMA(1, 1, At, B1); PG8_BAR; PG8_SCHED;
;             PG8_LDB(B0, 1, 0); PG8_LDB(B1, 1, 1); PG8_SCHED; PG8_LDA(At, 1, 0); PG8_STAGE(PG8_SA(0, 1), a2 + hstepA, voffA);
;             PG8_WAIT_V(8); PG8_WAIT_L(0); PG8_BAR; PG8_MMA(0, 0, At, B0); PG8_MMA(0, 1, At, B1); PG8_BAR; PG8_SCHED;
	s_setprio 1
	s_waitcnt lgkmcnt(0)
	v_mfma_f32_16x16x32_bf16 v[60:63], v[132:135], v[192:195], v[60:63]
	v_mfma_f32_16x16x32_bf16 v[56:59], v[142:145], v[192:195], v[56:59]
	v_mfma_f32_16x16x32_bf16 v[44:47], v[132:135], v[200:203], v[44:47]
	v_mfma_f32_16x16x32_bf16 v[40:43], v[142:145], v[200:203], v[40:43]
	v_mfma_f32_16x16x32_bf16 v[28:31], v[132:135], v[208:211], v[28:31]
	v_mfma_f32_16x16x32_bf16 v[24:27], v[142:145], v[208:211], v[24:27]
	v_mfma_f32_16x16x32_bf16 v[12:15], v[132:135], v[216:219], v[12:15]
	v_mfma_f32_16x16x32_bf16 v[8:11], v[142:145], v[216:219], v[8:11]
	v_mfma_f32_16x16x32_bf16 v[60:63], v[136:139], v[196:199], v[60:63]
	v_mfma_f32_16x16x32_bf16 v[56:59], v[158:161], v[196:199], v[56:59]
	v_mfma_f32_16x16x32_bf16 v[44:47], v[136:139], v[204:207], v[44:47]
	v_mfma_f32_16x16x32_bf16 v[40:43], v[158:161], v[204:207], v[40:43]
	v_mfma_f32_16x16x32_bf16 v[28:31], v[136:139], v[212:215], v[28:31]
	v_mfma_f32_16x16x32_bf16 v[24:27], v[158:161], v[212:215], v[24:27]
	v_mfma_f32_16x16x32_bf16 v[12:15], v[136:139], v[220:223], v[12:15]
	v_mfma_f32_16x16x32_bf16 v[8:11], v[158:161], v[220:223], v[8:11]
	v_mfma_f32_16x16x32_bf16 v[52:55], v[176:179], v[192:195], v[52:55]
	v_mfma_f32_16x16x32_bf16 v[48:51], v[184:187], v[192:195], v[48:51]
	v_mfma_f32_16x16x32_bf16 v[36:39], v[176:179], v[200:203], v[36:39]
	v_mfma_f32_16x16x32_bf16 v[32:35], v[184:187], v[200:203], v[32:35]
	v_mfma_f32_16x16x32_bf16 v[20:23], v[176:179], v[208:211], v[20:23]
	v_mfma_f32_16x16x32_bf16 v[16:19], v[184:187], v[208:211], v[16:19]
	v_mfma_f32_16x16x32_bf16 v[4:7], v[176:179], v[216:219], v[4:7]
	v_mfma_f32_16x16x32_bf16 v[0:3], v[184:187], v[216:219], v[0:3]
	v_mfma_f32_16x16x32_bf16 v[52:55], v[180:183], v[196:199], v[52:55]
	v_mfma_f32_16x16x32_bf16 v[48:51], v[188:191], v[196:199], v[48:51]
	v_mfma_f32_16x16x32_bf16 v[36:39], v[180:183], v[204:207], v[36:39]
	v_mfma_f32_16x16x32_bf16 v[32:35], v[188:191], v[204:207], v[32:35]
	v_mfma_f32_16x16x32_bf16 v[20:23], v[180:183], v[212:215], v[20:23]
	v_mfma_f32_16x16x32_bf16 v[16:19], v[188:191], v[212:215], v[16:19]
	v_mfma_f32_16x16x32_bf16 v[4:7], v[180:183], v[220:223], v[4:7]
	v_mfma_f32_16x16x32_bf16 v[0:3], v[188:191], v[220:223], v[0:3]
	s_setprio 0
	s_barrier
	s_add_i32 s12, 0, 0x18000
	v_add_u32_e32 v80, s12, v173
	s_add_i32 s18, 0, 0x1c000
	ds_read_b128 v[132:135], v80
	ds_read_b128 v[136:139], v80 offset:1024
	ds_read_b128 v[142:145], v80 offset:2048
	ds_read_b128 v[158:161], v80 offset:3072
	v_add_u32_e32 v80, s18, v173
	ds_read_b128 v[176:179], v80
	ds_read_b128 v[180:183], v80 offset:1024
	ds_read_b128 v[184:187], v80 offset:2048
	ds_read_b128 v[188:191], v80 offset:3072
	s_add_u32 s0, s0, s7
	s_addc_u32 s1, s1, 0
	s_mov_b32 m0, s81
	ds_read_b128 v[192:195], v174 offset:32768
	ds_read_b128 v[196:199], v174 offset:33792
	ds_read_b128 v[200:203], v174 offset:34816
	ds_read_b128 v[204:207], v174 offset:35840
	ds_read_b128 v[208:211], v174 offset:36864
	ds_read_b128 v[212:215], v174 offset:37888
	ds_read_b128 v[216:219], v174 offset:38912
	ds_read_b128 v[220:223], v174 offset:39936
	global_load_lds_dwordx4 v150, s[0:1]
	s_mov_b32 m0, s82
	s_nop 0
	global_load_lds_dwordx4 v154, s[0:1]
	s_waitcnt vmcnt(8)
	s_waitcnt lgkmcnt(0)
	s_barrier
	s_setprio 1
	s_waitcnt lgkmcnt(0)
	v_mfma_f32_16x16x32_bf16 v[128:131], v[132:135], v[192:195], v[128:131]
	v_mfma_f32_16x16x32_bf16 v[124:127], v[142:145], v[192:195], v[124:127]
	v_mfma_f32_16x16x32_bf16 v[112:115], v[132:135], v[200:203], v[112:115]
	v_mfma_f32_16x16x32_bf16 v[108:111], v[142:145], v[200:203], v[108:111]
	v_mfma_f32_16x16x32_bf16 v[96:99], v[132:135], v[208:211], v[96:99]
	v_mfma_f32_16x16x32_bf16 v[92:95], v[142:145], v[208:211], v[92:95]
	v_mfma_f32_16x16x32_bf16 v[76:79], v[132:135], v[216:219], v[76:79]
	v_mfma_f32_16x16x32_bf16 v[72:75], v[142:145], v[216:219], v[72:75]
	v_mfma_f32_16x16x32_bf16 v[128:131], v[136:139], v[196:199], v[128:131]
	v_mfma_f32_16x16x32_bf16 v[124:127], v[158:161], v[196:199], v[124:127]
	v_mfma_f32_16x16x32_bf16 v[112:115], v[136:139], v[204:207], v[112:115]
	v_mfma_f32_16x16x32_bf16 v[108:111], v[158:161], v[204:207], v[108:111]
	v_mfma_f32_16x16x32_bf16 v[96:99], v[136:139], v[212:215], v[96:99]
	v_mfma_f32_16x16x32_bf16 v[92:95], v[158:161], v[212:215], v[92:95]
	v_mfma_f32_16x16x32_bf16 v[76:79], v[136:139], v[220:223], v[76:79]
	v_mfma_f32_16x16x32_bf16 v[72:75], v[158:161], v[220:223], v[72:75]
	v_mfma_f32_16x16x32_bf16 v[120:123], v[176:179], v[192:195], v[120:123]
	v_mfma_f32_16x16x32_bf16 v[116:119], v[184:187], v[192:195], v[116:119]
	v_mfma_f32_16x16x32_bf16 v[104:107], v[176:179], v[200:203], v[104:107]
	v_mfma_f32_16x16x32_bf16 v[100:103], v[184:187], v[200:203], v[100:103]
	v_mfma_f32_16x16x32_bf16 v[86:89], v[176:179], v[208:211], v[88:91]
	v_mfma_f32_16x16x32_bf16 v[82:85], v[184:187], v[208:211], v[82:85]
	v_mfma_f32_16x16x32_bf16 v[68:71], v[176:179], v[216:219], v[68:71]
	v_mfma_f32_16x16x32_bf16 v[64:67], v[184:187], v[216:219], v[64:67]
	v_mfma_f32_16x16x32_bf16 v[120:123], v[180:183], v[196:199], v[120:123]
	v_mfma_f32_16x16x32_bf16 v[116:119], v[188:191], v[196:199], v[116:119]
	v_mfma_f32_16x16x32_bf16 v[104:107], v[180:183], v[204:207], v[104:107]
	v_mfma_f32_16x16x32_bf16 v[100:103], v[188:191], v[204:207], v[100:103]
	v_mfma_f32_16x16x32_bf16 v[88:91], v[180:183], v[212:215], v[86:89]
	v_mfma_f32_16x16x32_bf16 v[84:87], v[188:191], v[212:215], v[82:85]
	v_mfma_f32_16x16x32_bf16 v[68:71], v[180:183], v[220:223], v[68:71]
	v_mfma_f32_16x16x32_bf16 v[64:67], v[188:191], v[220:223], v[64:67]
	s_setprio 0
	s_barrier
; #define PG8_STAGE(bufoff, gbase, voff) do { _Pragma("unroll") for (int _i = 0; _i < 2; ++_i) \
;         __builtin_amdgcn_global_load_lds((const unsigned*)((const char*)(gbase) + (voff)[_i]), (LAS unsigned*)(lds + (bufoff) + ldsw + _i * 8192), 16, 0, 0); } while (0)
; #define PG8_LDA(dst, b, h) do { _Pragma("unroll") for (int m = 0; m < 4; ++m) _Pragma("unroll") for (int k = 0; k < 2; ++k) dst[m][k] = *(const LAS bf16x8*)(lds + PG8_SA(b, h) + aoff + m * 2048 + k * 1024); } while (0)
; #define PG8_MMA(ai, bj, At, Bt) do { __builtin_amdgcn_s_setprio(1); _Pragma("unroll") for (int m = 0; m < 4; ++m) _Pragma("unroll") for (int n = 0; n < 2; ++n) _Pragma("unroll") for (int k = 0; k < 2; ++k) \
;         acc[ai][bj][m][n] = __builtin_amdgcn_mfma_f32_16x16x32_bf16(Bt[n][k], At[m][k], acc[ai][bj][m][n], 0, 0, 0); __builtin_amdgcn_s_setprio(0); } while (0)
; #define PG8_WAIT_V(n) asm volatile("s_waitcnt vmcnt(" #n ")" ::: "memory")
; #define PG8_WAIT_L(n) asm volatile("s_waitcnt lgkmcnt(" #n ")" ::: "memory")
; #define PG8_BAR __builtin_amdgcn_s_barrier()
; #define PG8_SCHED __builtin_amdgcn_sched_barrier(0)
; DI void gemm_phase(LAS unsigned char* lds, int ph, unsigned char* ws, unsigned char* wg, int l, const float* pscale, int G, int cidx, int nx) {
;     ...
;             PG8_LDA(At, 1, 1); PG8_STAGE(PG8_SB(1, 0), b3, voffB); PG8_STAGE(PG8_SB(1, 1), b3 + hstepB, voffB); PG8_STAGE(PG8_SA(1, 0), a3, voffA);
;             PG8_WAIT_V(8); PG8_WAIT_L(0); PG8_BAR; PG8_MMA(1, 0, At, B0); PG8_MMA(1, 1, At, B1); PG8_BAR; PG8_SCHED;
;         }
	s_sub_u32 s20, s0, s7
	s_subb_u32 s21, s1, 0
	s_add_u32 s20, s20, s4
	s_addc_u32 s21, s21, s5
	s_add_u32 s0, s64, s4
	s_addc_u32 s1, s65, s5
	s_add_i32 s19, s12, s78
	s_mov_b32 m0, s19
	ds_read_b128 v[192:195], v174 offset:49152
	ds_read_b128 v[196:199], v174 offset:50176
	ds_read_b128 v[200:203], v174 offset:51200
	ds_read_b128 v[204:207], v174 offset:52224
	ds_read_b128 v[208:211], v174 offset:53248
	ds_read_b128 v[212:215], v174 offset:54272
	ds_read_b128 v[216:219], v174 offset:55296
	ds_read_b128 v[220:223], v174 offset:56320
	global_load_lds_dwordx4 v152, s[0:1]
	s_add_i32 m0, s19, 0x2000
	s_add_i32 s19, s18, s78
	global_load_lds_dwordx4 v156, s[0:1]
	s_add_u32 s0, s0, s77
	s_addc_u32 s1, s1, 0
	s_mov_b32 m0, s19
	s_nop 0
	global_load_lds_dwordx4 v152, s[0:1]
	s_add_i32 m0, s19, 0x2000
	s_nop 0
	global_load_lds_dwordx4 v156, s[0:1]
	s_mov_b32 m0, s93
	s_nop 0
	global_load_lds_dwordx4 v150, s[20:21]
	s_mov_b32 m0, s94
	s_nop 0
	global_load_lds_dwordx4 v154, s[20:21]
	s_waitcnt vmcnt(8)
	s_waitcnt lgkmcnt(0)
	s_barrier
	s_setprio 1
	s_waitcnt lgkmcnt(0)
	v_mfma_f32_16x16x32_bf16 v[60:63], v[132:135], v[192:195], v[60:63]
	v_mfma_f32_16x16x32_bf16 v[56:59], v[142:145], v[192:195], v[56:59]
	v_mfma_f32_16x16x32_bf16 v[44:47], v[132:135], v[200:203], v[44:47]
	v_mfma_f32_16x16x32_bf16 v[40:43], v[142:145], v[200:203], v[40:43]
	v_mfma_f32_16x16x32_bf16 v[28:31], v[132:135], v[208:211], v[28:31]
	v_mfma_f32_16x16x32_bf16 v[24:27], v[142:145], v[208:211], v[24:27]
	v_mfma_f32_16x16x32_bf16 v[12:15], v[132:135], v[216:219], v[12:15]
	v_mfma_f32_16x16x32_bf16 v[8:11], v[142:145], v[216:219], v[8:11]
	v_mfma_f32_16x16x32_bf16 v[60:63], v[136:139], v[196:199], v[60:63]
	v_mfma_f32_16x16x32_bf16 v[56:59], v[158:161], v[196:199], v[56:59]
	v_mfma_f32_16x16x32_bf16 v[44:47], v[136:139], v[204:207], v[44:47]
	v_mfma_f32_16x16x32_bf16 v[40:43], v[158:161], v[204:207], v[40:43]
	v_mfma_f32_16x16x32_bf16 v[28:31], v[136:139], v[212:215], v[28:31]
	v_mfma_f32_16x16x32_bf16 v[24:27], v[158:161], v[212:215], v[24:27]
	v_mfma_f32_16x16x32_bf16 v[12:15], v[136:139], v[220:223], v[12:15]
	v_mfma_f32_16x16x32_bf16 v[8:11], v[158:161], v[220:223], v[8:11]
	v_mfma_f32_16x16x32_bf16 v[52:55], v[176:179], v[192:195], v[52:55]
	v_mfma_f32_16x16x32_bf16 v[48:51], v[184:187], v[192:195], v[48:51]
	v_mfma_f32_16x16x32_bf16 v[36:39], v[176:179], v[200:203], v[36:39]
	v_mfma_f32_16x16x32_bf16 v[32:35], v[184:187], v[200:203], v[32:35]
	v_mfma_f32_16x16x32_bf16 v[20:23], v[176:179], v[208:211], v[20:23]
	v_mfma_f32_16x16x32_bf16 v[16:19], v[184:187], v[208:211], v[16:19]
	v_mfma_f32_16x16x32_bf16 v[4:7], v[176:179], v[216:219], v[4:7]
	v_mfma_f32_16x16x32_bf16 v[0:3], v[184:187], v[216:219], v[0:3]
	v_mfma_f32_16x16x32_bf16 v[52:55], v[180:183], v[196:199], v[52:55]
	v_mfma_f32_16x16x32_bf16 v[48:51], v[188:191], v[196:199], v[48:51]
	v_mfma_f32_16x16x32_bf16 v[36:39], v[180:183], v[204:207], v[36:39]
	v_mfma_f32_16x16x32_bf16 v[32:35], v[188:191], v[204:207], v[32:35]
	v_mfma_f32_16x16x32_bf16 v[20:23], v[180:183], v[212:215], v[20:23]
	v_mfma_f32_16x16x32_bf16 v[16:19], v[188:191], v[212:215], v[16:19]
	v_mfma_f32_16x16x32_bf16 v[4:7], v[180:183], v[220:223], v[4:7]
	v_mfma_f32_16x16x32_bf16 v[0:3], v[188:191], v[220:223], v[0:3]
	s_setprio 0
	s_barrier
	s_add_i32 s38, s38, 2
	s_cmp_ge_u32 s38, s75
	s_cbranch_scc1 .LBB0_507
